# v37 plus nt cache policy on the read-once G1 conv row loads
# baseline (speedup 1.0000x reference)
; DI float bflo(unsigned w) { return __uint_as_float(w << 16); }
; DI float bfhi(unsigned w) { return __uint_as_float(w & 0xffff0000u); }
; DI void g1_team(const Params& p, int j, int unit, lptr lds) {
;     ...
;     if (lw < 3) {
;         const int rb = lt / 48, cg = lt % 48, part = cg >> 4, sub = cg & 15;
;         const int col = part * 512 + h * 128 + sub * 8, t0 = 64 * n + rb * 16;
;         f32x4 wl[4][2];
; #pragma unroll
;         for (int i = 0; i < 4; ++i) { wl[i][0] = *(const f32x4*)(cw + i * 1536 + col); wl[i][1] = *(const f32x4*)(cw + i * 1536 + col + 4); }
;         u32x4 xr[19];
; #pragma unroll
;         for (int q = 0; q < 19; ++q) { const int tt = t0 - 3 + q; const int tc = tt < 0 ? 0 : tt;
;             u32x4 v = *(const u32x4*)(P + ((size_t)b * SEQ + tc) * PE + col);
;             if (tt < 0) v = (u32x4){0u, 0u, 0u, 0u};
;             xr[q] = v; }
; #pragma unroll
;         for (int i = 0; i < 16; ++i) {
;             float acc[8]; for (int e = 0; e < 8; ++e) acc[e] = 0.f;
; #pragma unroll
;             for (int tp = 0; tp < 4; ++tp) { const u32x4 x = xr[i + tp]; const f32x4 w0 = wl[tp][0], w1 = wl[tp][1];
;                 acc[0] += w0[0] * bflo(x.x); acc[1] += w0[1] * bfhi(x.x); acc[2] += w0[2] * bflo(x.y); acc[3] += w0[3] * bfhi(x.y);
;                 acc[4] += w1[0] * bflo(x.z); acc[5] += w1[1] * bfhi(x.z); acc[6] += w1[2] * bflo(x.w); acc[7] += w1[3] * bfhi(x.w); }
.LBB0_365:
	s_or_b64 exec, exec, s[42:43]
	s_bfe_u32 s42, s39, 0x20006
	s_cmp_eq_u32 s42, 3
	s_cbranch_scc1 .LBB0_399
	s_movk_i32 s10, 0xab
	v_mul_lo_u16_sdwa v0, v136, s10 dst_sel:DWORD dst_unused:UNUSED_PAD src0_sel:BYTE_0 src1_sel:DWORD
	v_lshrrev_b16_e32 v137, 13, v0
	v_mul_lo_u16_e32 v0, 48, v137
	v_sub_u16_e32 v98, v136, v0
	v_bfe_u32 v109, v98, 4, 4
	v_and_b32_e32 v113, 15, v98
	v_lshlrev_b32_e32 v0, 9, v109
	s_lshl_b32 s3, s3, 7
	v_lshlrev_b32_e32 v2, 3, v113
	v_or3_b32 v35, v0, s3, v2
	v_lshlrev_b32_e32 v0, 2, v35
	s_lshl_b32 s10, s2, 6
	v_lshl_add_u64 v[14:15], s[0:1], 0, v[0:1]
	s_mov_b64 s[2:3], 0x1800
	v_lshl_add_u64 v[6:7], v[14:15], 0, s[2:3]
	s_movk_i32 s2, 0x1000
	v_add_co_u32_e32 v8, vcc, s2, v14
	s_mov_b64 s[2:3], 0x3000
	s_nop 0
	v_addc_co_u32_e32 v9, vcc, 0, v15, vcc
	v_lshl_add_u64 v[10:11], v[14:15], 0, s[2:3]
	s_movk_i32 s2, 0x3000
	v_add_co_u32_e32 v12, vcc, s2, v14
	s_mov_b64 s[2:3], 0x4800
	v_lshl_add_u32 v34, v137, 4, s10
	global_load_dwordx4 v[18:21], v0, s[0:1]
	global_load_dwordx4 v[2:5], v0, s[0:1] offset:16
	v_addc_co_u32_e32 v13, vcc, 0, v15, vcc
	v_lshl_add_u64 v[16:17], v[14:15], 0, s[2:3]
	s_movk_i32 s2, 0x4000
	v_add_u32_e32 v42, -3, v34
	s_ashr_i32 s41, s40, 31
	v_lshlrev_b32_e32 v0, 1, v35
	v_add_co_u32_e32 v14, vcc, s2, v14
	s_lshl_b64 s[2:3], s[40:41], 12
	v_lshl_add_u64 v[36:37], s[4:5], 0, v[0:1]
	v_max_i32_e32 v0, 0, v42
	v_lshl_add_u64 v[38:39], s[2:3], 0, v[0:1]
	v_mad_u64_u32 v[40:41], s[10:11], v38, s95, v[36:37]
	v_addc_co_u32_e32 v15, vcc, 0, v15, vcc
	v_mad_i32_i24 v41, v39, s95, v41
	global_load_dwordx4 v[22:25], v[8:9], off offset:2048
	s_nop 0
	global_load_dwordx4 v[6:9], v[6:7], off offset:16
	s_nop 0
	global_load_dwordx4 v[26:29], v[12:13], off
	s_nop 0
	global_load_dwordx4 v[10:13], v[10:11], off offset:16
	s_nop 0
	global_load_dwordx4 v[30:33], v[14:15], off offset:2048
	s_nop 0
	global_load_dwordx4 v[14:17], v[16:17], off offset:16
	v_max_i32_e32 v0, -1, v42
	global_load_dwordx4 v[38:41], v[40:41], off nt
	v_mov_b32_e32 v159, 0
	v_add_u32_e32 v158, 1, v0
	v_lshl_add_u64 v[160:161], s[2:3], 0, v[158:159]
	v_mad_u64_u32 v[162:163], s[10:11], v160, s95, v[36:37]
	v_mad_i32_i24 v163, v161, s95, v163
	global_load_dwordx4 v[164:167], v[162:163], off nt
	v_add_u32_e32 v158, -1, v34
	v_max_i32_e32 v158, 0, v158
	v_lshl_add_u64 v[160:161], s[2:3], 0, v[158:159]
	v_mad_u64_u32 v[162:163], s[10:11], v160, s95, v[36:37]
	v_mad_i32_i24 v163, v161, s95, v163
	global_load_dwordx4 v[168:171], v[162:163], off nt
	v_mov_b32_e32 v158, v34
	v_lshl_add_u64 v[160:161], s[2:3], 0, v[158:159]
	v_mad_u64_u32 v[162:163], s[10:11], v160, s95, v[36:37]
	v_mad_i32_i24 v163, v161, s95, v163
	v_mov_b32_e32 v172, s95
	v_mov_b32_e32 v173, 0
	global_load_dwordx4 v[94:97], v[162:163], off nt
	v_lshl_add_u64 v[162:163], v[162:163], 0, v[172:173]
	global_load_dwordx4 v[90:93], v[162:163], off nt
	v_lshl_add_u64 v[162:163], v[162:163], 0, v[172:173]
	global_load_dwordx4 v[86:89], v[162:163], off nt
	v_lshl_add_u64 v[162:163], v[162:163], 0, v[172:173]
	global_load_dwordx4 v[82:85], v[162:163], off nt
	v_lshl_add_u64 v[162:163], v[162:163], 0, v[172:173]
	global_load_dwordx4 v[78:81], v[162:163], off nt
	v_lshl_add_u64 v[162:163], v[162:163], 0, v[172:173]
	global_load_dwordx4 v[74:77], v[162:163], off nt
	v_lshl_add_u64 v[162:163], v[162:163], 0, v[172:173]
	global_load_dwordx4 v[70:73], v[162:163], off nt
	v_lshl_add_u64 v[162:163], v[162:163], 0, v[172:173]
	global_load_dwordx4 v[66:69], v[162:163], off nt
	v_lshl_add_u64 v[162:163], v[162:163], 0, v[172:173]
	global_load_dwordx4 v[62:65], v[162:163], off nt
	v_lshl_add_u64 v[162:163], v[162:163], 0, v[172:173]
	global_load_dwordx4 v[58:61], v[162:163], off nt
	v_lshl_add_u64 v[162:163], v[162:163], 0, v[172:173]
	global_load_dwordx4 v[54:57], v[162:163], off nt
	v_lshl_add_u64 v[162:163], v[162:163], 0, v[172:173]
	global_load_dwordx4 v[50:53], v[162:163], off nt
	v_lshl_add_u64 v[162:163], v[162:163], 0, v[172:173]
	global_load_dwordx4 v[46:49], v[162:163], off nt
	v_cmp_eq_u32_e32 vcc, 0, v34
	v_add_u32_e32 v0, 1, v0
	v_mov_b32_e32 v35, v1
	v_cmp_lt_u16_sdwa s[40:41], v98, v206 src0_sel:BYTE_0 src1_sel:DWORD
	s_waitcnt vmcnt(22)
	v_mov_b32_e32 v114, v4
	s_waitcnt vmcnt(20)
	v_mov_b32_e32 v115, v8
	s_waitcnt vmcnt(18)
	v_mov_b32_e32 v119, v12
	s_waitcnt vmcnt(16)
	v_mov_b32_e32 v118, v16
	v_mov_b32_e32 v127, v13
	s_waitcnt vmcnt(15)
	v_cndmask_b32_e64 v130, v39, 0, vcc
	v_cndmask_b32_e64 v131, v38, 0, vcc
	v_lshl_add_u64 v[38:39], s[2:3], 0, v[0:1]
	v_cndmask_b32_e64 v132, v40, 0, vcc
	v_cndmask_b32_e64 v100, v41, 0, vcc
	v_mad_u64_u32 v[40:41], s[10:11], v38, s95, v[36:37]
	v_mad_i32_i24 v41, v39, s95, v41
	v_add_u32_e32 v0, -1, v34
	v_max_i32_e32 v0, 0, v0
	v_lshlrev_b32_e32 v98, 16, v100
	v_and_b32_e32 v100, 0xffff0000, v100
	s_waitcnt vmcnt(14)
	v_cndmask_b32_e64 v102, v165, 0, vcc
	v_cndmask_b32_e64 v103, v164, 0, vcc
	v_lshl_add_u64 v[38:39], s[2:3], 0, v[0:1]
	v_cndmask_b32_e64 v101, v167, 0, vcc
	v_cndmask_b32_e64 v99, v166, 0, vcc
	v_mad_u64_u32 v[40:41], s[10:11], v38, s95, v[36:37]
	v_mad_i32_i24 v41, v39, s95, v41
	v_or_b32_e32 v0, 1, v34
	v_lshlrev_b32_e32 v108, 16, v101
	v_lshlrev_b32_e32 v110, 16, v99
	v_and_b32_e32 v111, 0xffff0000, v99
	v_mov_b32_e32 v99, v108
	v_pk_mul_f32 v[98:99], v[114:115], v[98:99]
	v_lshlrev_b32_e32 v128, 16, v103
	v_and_b32_e32 v129, 0xffff0000, v103
	v_lshlrev_b32_e32 v116, 16, v102
	v_and_b32_e32 v117, 0xffff0000, v102
	v_and_b32_e32 v112, 0xffff0000, v101
	v_mov_b32_e32 v101, v112
	s_waitcnt vmcnt(13)
; DI float bflo(unsigned w) { return __uint_as_float(w << 16); }
; DI float bfhi(unsigned w) { return __uint_as_float(w & 0xffff0000u); }
; DI float sigmoidf_(float x) { return 1.f / (1.f + __expf(-x)); }
; DI void g1_team(const Params& p, int j, int unit, lptr lds) {
;     ...
;         for (int q = 0; q < 19; ++q) { const int tt = t0 - 3 + q; const int tc = tt < 0 ? 0 : tt;
;             u32x4 v = *(const u32x4*)(P + ((size_t)b * SEQ + tc) * PE + col);
;             if (tt < 0) v = (u32x4){0u, 0u, 0u, 0u};
;             xr[q] = v; }
; #pragma unroll
;         for (int i = 0; i < 16; ++i) {
;             float acc[8]; for (int e = 0; e < 8; ++e) acc[e] = 0.f;
; #pragma unroll
;             for (int tp = 0; tp < 4; ++tp) { const u32x4 x = xr[i + tp]; const f32x4 w0 = wl[tp][0], w1 = wl[tp][1];
;                 acc[0] += w0[0] * bflo(x.x); acc[1] += w0[1] * bfhi(x.x); acc[2] += w0[2] * bflo(x.y); acc[3] += w0[3] * bfhi(x.y);
;                 acc[4] += w1[0] * bflo(x.z); acc[5] += w1[1] * bfhi(x.z); acc[6] += w1[2] * bflo(x.w); acc[7] += w1[3] * bfhi(x.w); }
;             float ss = 0.f;
;             for (int e = 0; e < 8; ++e) { acc[e] = acc[e] * sigmoidf_(acc[e]); ss += acc[e] * acc[e]; }
	v_cndmask_b32_e64 v105, v169, 0, vcc
	v_cndmask_b32_e64 v106, v168, 0, vcc
	v_lshl_add_u64 v[38:39], s[2:3], 0, v[34:35]
	v_cndmask_b32_e64 v104, v170, 0, vcc
	v_cndmask_b32_e64 v126, v171, 0, vcc
	v_mad_u64_u32 v[40:41], s[10:11], v38, s95, v[36:37]
	v_mad_i32_i24 v41, v39, s95, v41
	v_lshl_add_u64 v[38:39], s[2:3], 0, v[0:1]
	v_mad_u64_u32 v[40:41], s[10:11], v38, s95, v[36:37]
	v_or_b32_e32 v0, 2, v34
	v_mad_i32_i24 v41, v39, s95, v41
	v_lshl_add_u64 v[38:39], s[2:3], 0, v[0:1]
	v_mad_u64_u32 v[40:41], s[10:11], v38, s95, v[36:37]
	v_or_b32_e32 v0, 3, v34
	v_mad_i32_i24 v41, v39, s95, v41
	v_lshl_add_u64 v[38:39], s[2:3], 0, v[0:1]
	v_mad_u64_u32 v[40:41], s[10:11], v38, s95, v[36:37]
	v_or_b32_e32 v0, 4, v34
	v_mad_i32_i24 v41, v39, s95, v41
	v_lshl_add_u64 v[38:39], s[2:3], 0, v[0:1]
	v_mad_u64_u32 v[40:41], s[10:11], v38, s95, v[36:37]
	v_or_b32_e32 v0, 5, v34
	v_mad_i32_i24 v41, v39, s95, v41
	v_lshl_add_u64 v[38:39], s[2:3], 0, v[0:1]
	v_mad_u64_u32 v[40:41], s[10:11], v38, s95, v[36:37]
	v_or_b32_e32 v0, 6, v34
	v_mad_i32_i24 v41, v39, s95, v41
	v_lshl_add_u64 v[38:39], s[2:3], 0, v[0:1]
	v_mad_u64_u32 v[40:41], s[10:11], v38, s95, v[36:37]
	v_or_b32_e32 v0, 7, v34
	v_mad_i32_i24 v41, v39, s95, v41
	v_lshl_add_u64 v[38:39], s[2:3], 0, v[0:1]
	v_mad_u64_u32 v[40:41], s[10:11], v38, s95, v[36:37]
	v_or_b32_e32 v0, 8, v34
	v_mad_i32_i24 v41, v39, s95, v41
	v_lshl_add_u64 v[38:39], s[2:3], 0, v[0:1]
	v_mad_u64_u32 v[40:41], s[10:11], v38, s95, v[36:37]
	v_or_b32_e32 v0, 9, v34
	v_mad_i32_i24 v41, v39, s95, v41
	v_lshl_add_u64 v[38:39], s[2:3], 0, v[0:1]
	v_mad_u64_u32 v[40:41], s[10:11], v38, s95, v[36:37]
	v_or_b32_e32 v0, 10, v34
	v_mad_i32_i24 v41, v39, s95, v41
	v_lshl_add_u64 v[38:39], s[2:3], 0, v[0:1]
	v_mad_u64_u32 v[40:41], s[10:11], v38, s95, v[36:37]
	v_or_b32_e32 v0, 11, v34
	v_mad_i32_i24 v41, v39, s95, v41
	v_lshl_add_u64 v[38:39], s[2:3], 0, v[0:1]
	v_mad_u64_u32 v[40:41], s[10:11], v38, s95, v[36:37]
	v_or_b32_e32 v0, 12, v34
	v_mad_i32_i24 v41, v39, s95, v41
	v_lshl_add_u64 v[38:39], s[2:3], 0, v[0:1]
	v_mad_u64_u32 v[40:41], s[10:11], v38, s95, v[36:37]
	v_or_b32_e32 v0, 13, v34
	v_mad_i32_i24 v41, v39, s95, v41
	v_lshl_add_u64 v[38:39], s[2:3], 0, v[0:1]
	v_mad_u64_u32 v[40:41], s[10:11], v38, s95, v[36:37]
	v_or_b32_e32 v0, 14, v34
	v_mad_i32_i24 v41, v39, s95, v41
	v_lshl_add_u64 v[38:39], s[2:3], 0, v[0:1]
	v_or_b32_e32 v0, 15, v34
	v_lshl_add_u64 v[34:35], s[2:3], 0, v[0:1]
	v_add_f32_e32 v0, 0, v98
	s_waitcnt vmcnt(12)
	v_lshlrev_b32_e32 v102, 16, v97
	v_lshlrev_b32_e32 v103, 16, v126
	v_add_f32_e32 v0, v0, v99
	v_mov_b32_e32 v98, v5
	v_mov_b32_e32 v99, v9
	v_lshlrev_b32_e32 v124, 16, v106
	v_and_b32_e32 v125, 0xffff0000, v106
	v_pk_mul_f32 v[106:107], v[118:119], v[102:103]
	v_pk_mul_f32 v[100:101], v[98:99], v[100:101]
	v_add_f32_e32 v0, v0, v107
	v_add_f32_e32 v100, 0, v100
	v_add_f32_e32 v144, v106, v0
	v_and_b32_e32 v107, 0xffff0000, v126
	v_and_b32_e32 v106, 0xffff0000, v97
	v_mov_b32_e32 v126, v17
	v_add_f32_e32 v133, v100, v101
	v_lshlrev_b32_e32 v122, 16, v105
	v_and_b32_e32 v123, 0xffff0000, v105
	v_lshlrev_b32_e32 v120, 16, v104
	v_and_b32_e32 v121, 0xffff0000, v104
	v_lshlrev_b32_e32 v104, 16, v94
	v_and_b32_e32 v105, 0xffff0000, v94
	v_lshlrev_b32_e32 v100, 16, v95
	v_and_b32_e32 v101, 0xffff0000, v95
	v_lshlrev_b32_e32 v94, 16, v96
	v_and_b32_e32 v95, 0xffff0000, v96
	v_pk_mul_f32 v[96:97], v[126:127], v[106:107]
	global_load_dwordx4 v[42:45], v[40:41], off nt
	v_add_f32_e32 v0, v133, v97
	v_add_f32_e32 v0, v96, v0
	v_lshlrev_b32_e32 v96, 16, v131
	v_and_b32_e32 v97, 0xffff0000, v131
	v_pk_fma_f32 v[96:97], v[18:19], v[96:97], 0 op_sel_hi:[1,1,0]
	v_mad_u64_u32 v[40:41], s[10:11], v38, s95, v[36:37]
	v_pk_fma_f32 v[96:97], v[22:23], v[128:129], v[96:97]
	v_mad_u64_u32 v[36:37], s[2:3], v34, s95, v[36:37]
	v_pk_fma_f32 v[96:97], v[26:27], v[124:125], v[96:97]
	v_mad_i32_i24 v41, v39, s95, v41
	v_pk_fma_f32 v[96:97], v[30:31], v[104:105], v[96:97]
	v_mad_i32_i24 v37, v35, s95, v37
	v_mul_f32_e32 v131, 0xbfb8aa3b, v96
	v_exp_f32_e32 v138, v131
	v_mul_f32_e32 v131, 0xbfb8aa3b, v97
	v_exp_f32_e32 v139, v131
	global_load_dwordx4 v[38:41], v[40:41], off nt
	v_pk_add_f32 v[138:139], v[138:139], 1.0 op_sel_hi:[1,0]
	s_nop 0
	v_div_scale_f32 v131, s[2:3], v139, v139, 1.0
	v_rcp_f32_e32 v133, v131
	global_load_dwordx4 v[34:37], v[36:37], off nt
	v_fma_f32 v140, -v131, v133, 1.0
	v_fmac_f32_e32 v133, v140, v133
	v_div_scale_f32 v140, vcc, 1.0, v139, 1.0
	v_mul_f32_e32 v141, v140, v133
	v_fma_f32 v142, -v131, v141, v140
	v_fmac_f32_e32 v141, v142, v133
	v_fma_f32 v131, -v131, v141, v140
	v_div_fmas_f32 v131, v131, v133, v141
	v_div_fixup_f32 v139, v131, v139, 1.0
	v_div_scale_f32 v131, s[2:3], v138, v138, 1.0
	v_rcp_f32_e32 v133, v131
	s_nop 0
	v_fma_f32 v140, -v131, v133, 1.0
	v_fmac_f32_e32 v133, v140, v133
	v_div_scale_f32 v140, vcc, 1.0, v138, 1.0
	v_mul_f32_e32 v141, v140, v133
	v_fma_f32 v142, -v131, v141, v140
	v_fmac_f32_e32 v141, v142, v133
	v_fma_f32 v131, -v131, v141, v140
	v_div_fmas_f32 v131, v131, v133, v141
	v_lshlrev_b32_e32 v140, 16, v130
	v_and_b32_e32 v141, 0xffff0000, v130
	v_div_fixup_f32 v138, v131, v138, 1.0
	v_pk_fma_f32 v[130:131], v[20:21], v[140:141], 0 op_sel_hi:[1,1,0]
	v_pk_mul_f32 v[96:97], v[96:97], v[138:139]
	v_pk_fma_f32 v[130:131], v[24:25], v[116:117], v[130:131]
; DI unsigned pk2(float lo, float hi) { f32x2_t v = {lo, hi}; bf16x2_t b = __builtin_convertvector(v, bf16x2_t); return __builtin_bit_cast(unsigned, b); }
; DI float shx(float v, int m) { const int lane = tid_() & 63; return __builtin_bit_cast(float, __builtin_amdgcn_ds_bpermute((lane ^ m) << 2, __builtin_bit_cast(int, v))); }
; DI float sigmoidf_(float x) { return 1.f / (1.f + __expf(-x)); }
; DI void g1_team(const Params& p, int j, int unit, lptr lds) {
;     ...
;             float ss = 0.f;
;             for (int e = 0; e < 8; ++e) { acc[e] = acc[e] * sigmoidf_(acc[e]); ss += acc[e] * acc[e]; }
;             ss += shx(ss, 1); ss += shx(ss, 2); ss += shx(ss, 4); ss += shx(ss, 8);
;             if (part < 2) { const float rn = rsqrtf(ss + EPS); for (int e = 0; e < 8; ++e) acc[e] *= rn; }
;             u32x4 o; o.x = pk2(acc[0], acc[1]); o.y = pk2(acc[2], acc[3]); o.z = pk2(acc[4], acc[5]); o.w = pk2(acc[6], acc[7]);
;             lst<u32x4>(lds, part * 17408 + (rb * 16 + i) * 272 + sub * 16, o);
	v_pk_mul_f32 v[138:139], v[96:97], v[96:97]
	v_pk_fma_f32 v[130:131], v[28:29], v[122:123], v[130:131]
	v_add_f32_e32 v138, v138, v139
	v_pk_fma_f32 v[130:131], v[32:33], v[100:101], v[130:131]
	s_nop 0
	v_mul_f32_e32 v133, 0xbfb8aa3b, v130
	v_exp_f32_e32 v140, v133
	v_mul_f32_e32 v133, 0xbfb8aa3b, v131
	v_exp_f32_e32 v141, v133
	s_nop 0
	v_pk_add_f32 v[140:141], v[140:141], 1.0 op_sel_hi:[1,0]
	s_nop 0
	v_div_scale_f32 v133, s[2:3], v141, v141, 1.0
	v_rcp_f32_e32 v142, v133
	s_nop 0
	v_fma_f32 v143, -v133, v142, 1.0
	v_fmac_f32_e32 v142, v143, v142
	v_div_scale_f32 v143, vcc, 1.0, v141, 1.0
	v_mul_f32_e32 v145, v143, v142
	v_fma_f32 v146, -v133, v145, v143
	v_fmac_f32_e32 v145, v146, v142
	v_fma_f32 v133, -v133, v145, v143
	v_div_fmas_f32 v133, v133, v142, v145
	v_div_fixup_f32 v141, v133, v141, 1.0
	v_div_scale_f32 v133, s[2:3], v140, v140, 1.0
	v_rcp_f32_e32 v142, v133
	s_nop 0
	v_fma_f32 v143, -v133, v142, 1.0
	v_fmac_f32_e32 v142, v143, v142
	v_div_scale_f32 v143, vcc, 1.0, v140, 1.0
	v_mul_f32_e32 v145, v143, v142
	v_fma_f32 v146, -v133, v145, v143
	v_fmac_f32_e32 v145, v146, v142
	v_fma_f32 v133, -v133, v145, v143
	v_div_fmas_f32 v133, v133, v142, v145
	v_lshlrev_b32_e32 v142, 16, v132
	v_and_b32_e32 v143, 0xffff0000, v132
	v_div_fixup_f32 v140, v133, v140, 1.0
	v_pk_fma_f32 v[132:133], v[2:3], v[142:143], 0 op_sel_hi:[1,1,0]
	v_pk_mul_f32 v[130:131], v[130:131], v[140:141]
	v_pk_fma_f32 v[132:133], v[6:7], v[110:111], v[132:133]
	v_pk_mul_f32 v[140:141], v[130:131], v[130:131]
	v_pk_fma_f32 v[132:133], v[10:11], v[120:121], v[132:133]
	v_add_f32_e32 v138, v140, v138
	v_pk_fma_f32 v[132:133], v[14:15], v[94:95], v[132:133]
	v_add_f32_e32 v138, v141, v138
	v_mul_f32_e32 v142, 0xbfb8aa3b, v132
	v_mul_f32_e32 v143, 0xbfb8aa3b, v133
	v_exp_f32_e32 v142, v142
	v_exp_f32_e32 v143, v143
	s_nop 0
	v_pk_add_f32 v[142:143], v[142:143], 1.0 op_sel_hi:[1,0]
	s_nop 0
	v_div_scale_f32 v145, s[2:3], v143, v143, 1.0
	v_rcp_f32_e32 v146, v145
	s_nop 0
	v_fma_f32 v147, -v145, v146, 1.0
	v_fmac_f32_e32 v146, v147, v146
	v_div_scale_f32 v147, vcc, 1.0, v143, 1.0
	v_mul_f32_e32 v153, v147, v146
	v_fma_f32 v154, -v145, v153, v147
	v_fmac_f32_e32 v153, v154, v146
	v_fma_f32 v145, -v145, v153, v147
	v_div_fmas_f32 v145, v145, v146, v153
	v_div_fixup_f32 v143, v145, v143, 1.0
	v_div_scale_f32 v145, s[2:3], v142, v142, 1.0
	v_rcp_f32_e32 v146, v145
	s_nop 0
	v_fma_f32 v147, -v145, v146, 1.0
	v_fmac_f32_e32 v146, v147, v146
	v_div_scale_f32 v147, vcc, 1.0, v142, 1.0
	v_mul_f32_e32 v153, v147, v146
	v_fma_f32 v154, -v145, v153, v147
	v_fmac_f32_e32 v153, v154, v146
	v_fma_f32 v145, -v145, v153, v147
	v_div_fmas_f32 v145, v145, v146, v153
	v_div_fixup_f32 v142, v145, v142, 1.0
	v_pk_mul_f32 v[132:133], v[132:133], v[142:143]
	s_nop 0
	v_pk_mul_f32 v[142:143], v[132:133], v[132:133]
	s_nop 0
	v_add_f32_e32 v138, v142, v138
	v_add_f32_e32 v140, v143, v138
	v_mul_f32_e32 v138, 0xbfb8aa3b, v144
	v_exp_f32_e32 v138, v138
	s_nop 0
	v_add_f32_e32 v138, 1.0, v138
	v_div_scale_f32 v139, s[2:3], v138, v138, 1.0
	v_rcp_f32_e32 v141, v139
	s_nop 0
	v_fma_f32 v142, -v139, v141, 1.0
	v_fmac_f32_e32 v141, v142, v141
	v_div_scale_f32 v142, vcc, 1.0, v138, 1.0
	v_mul_f32_e32 v143, v142, v141
	v_fma_f32 v145, -v139, v143, v142
	v_fmac_f32_e32 v143, v145, v141
	v_fma_f32 v139, -v139, v143, v142
	v_div_fmas_f32 v139, v139, v141, v143
	v_div_fixup_f32 v138, v139, v138, 1.0
	v_mul_f32_e32 v139, 0xbfb8aa3b, v0
	v_exp_f32_e32 v139, v139
	v_mul_f32_e32 v138, v144, v138
	v_fmac_f32_e32 v140, v138, v138
	v_add_f32_e32 v139, 1.0, v139
	v_div_scale_f32 v141, s[2:3], v139, v139, 1.0
	v_rcp_f32_e32 v142, v141
	s_nop 0
	v_fma_f32 v143, -v141, v142, 1.0
	v_fmac_f32_e32 v142, v143, v142
	v_div_scale_f32 v143, vcc, 1.0, v139, 1.0
	v_mul_f32_e32 v144, v143, v142
	v_fma_f32 v145, -v141, v144, v143
	v_fmac_f32_e32 v144, v145, v142
	v_fma_f32 v141, -v141, v144, v143
	v_div_fmas_f32 v141, v141, v142, v144
	v_div_fixup_f32 v139, v141, v139, 1.0
	v_mul_f32_e32 v139, v0, v139
	v_mov_b32_e32 v0, v194
	v_fmac_f32_e32 v140, v139, v139
	v_lshlrev_b32_e32 v0, 2, v0
	v_bitop3_b32 v0, v0, 4, v199 bitop3:0x6c
	ds_bpermute_b32 v0, v0, v140
	s_waitcnt lgkmcnt(0)
	v_add_f32_e32 v0, v140, v0
	v_mov_b32_e32 v140, v194
	s_nop 0
	v_lshlrev_b32_e32 v140, 2, v140
	v_bitop3_b32 v140, v140, 8, v199 bitop3:0x6c
	ds_bpermute_b32 v140, v140, v0
	s_waitcnt lgkmcnt(0)
	v_add_f32_e32 v0, v0, v140
	v_mov_b32_e32 v140, v194
	s_nop 0
	v_lshlrev_b32_e32 v140, 2, v140
	v_bitop3_b32 v140, v140, 16, v199 bitop3:0x6c
	ds_bpermute_b32 v140, v140, v0
	s_waitcnt lgkmcnt(0)
	v_add_f32_e32 v0, v0, v140
	v_mov_b32_e32 v140, v194
	s_nop 0
	v_lshlrev_b32_e32 v140, 2, v140
	v_bitop3_b32 v140, v140, 32, v199 bitop3:0x6c
	ds_bpermute_b32 v140, v140, v0
	s_and_saveexec_b64 s[2:3], s[40:41]
	s_cbranch_execz .LBB0_368
	s_waitcnt lgkmcnt(0)
	v_add_f32_e32 v0, v0, v140
	v_add_f32_e32 v0, 0x358637bd, v0
	v_mul_f32_e32 v140, 0x4b800000, v0
	v_cmp_gt_f32_e32 vcc, s72, v0
	s_nop 1
	v_cndmask_b32_e32 v0, v0, v140, vcc
	v_rsq_f32_e32 v0, v0
	s_nop 0
	v_mul_f32_e32 v140, 0x45800000, v0
	v_cndmask_b32_e32 v0, v0, v140, vcc
	v_pk_mul_f32 v[96:97], v[96:97], v[0:1] op_sel_hi:[1,0]
	v_pk_mul_f32 v[130:131], v[130:131], v[0:1] op_sel_hi:[1,0]
	v_pk_mul_f32 v[132:133], v[132:133], v[0:1] op_sel_hi:[1,0]
	v_mul_f32_e32 v138, v138, v0
	v_mul_f32_e32 v139, v139, v0
